# GEMM stage prologues: K-tile 1's LDS-DMA loads issued before waiting for K-tile 0 (wait+barrier moved behind them)
# speedup vs baseline: 1.0136x; 1.0060x over previous
.LBB0_359:
	s_and_b32 s36, s1, 3
	s_lshl_b32 s83, s2, 6
	s_lshl_b32 s1, s2, 13
	s_lshl_b32 s10, s36, 12
	v_readlane_b32 s12, v246, 2
	v_readlane_b32 s13, v246, 3
	s_add_u32 s38, s12, 0x7500000
	s_addc_u32 s39, s13, 0
	s_add_u32 s40, s12, 0x1be00000
	s_mov_b64 s[42:43], 0x80
	s_addc_u32 s41, s13, 0
	s_add_i32 m0, s31, 0x18000
	v_lshl_add_u64 v[8:9], v[8:9], 0, s[42:43]
	global_load_lds_dwordx4 v[8:9], off
	v_lshl_add_u64 v[4:5], v[4:5], 0, s[42:43]
	s_add_i32 m0, s31, 0x1a000
	s_add_i32 s84, s31, 0x8000
	s_add_i32 s85, s31, 0xa000
	global_load_lds_dwordx4 v[4:5], off
	v_lshl_add_u64 v[2:3], v[2:3], 0, s[42:43]
	s_mov_b32 m0, s84
	s_add_u32 s2, s8, 0x40080
	global_load_lds_dwordx4 v[2:3], off
	v_lshl_add_u64 v[2:3], v[6:7], 0, s[42:43]
	s_mov_b32 m0, s85
	s_addc_u32 s3, s9, 0
	global_load_lds_dwordx4 v[2:3], off
	s_add_i32 m0, s31, 0x1c000
	v_lshl_add_u64 v[2:3], s[2:3], 0, v[164:165]
	global_load_lds_dwordx4 v[2:3], off
	v_lshl_add_u64 v[2:3], s[2:3], 0, v[168:169]
	s_add_i32 m0, s31, 0x1e000
	v_and_b32_e32 v1, 15, v0
	global_load_lds_dwordx4 v[2:3], off
	s_waitcnt vmcnt(8)
	s_barrier
	v_bfe_u32 v2, v0, 4, 2
	v_lshlrev_b32_e32 v170, 4, v2
	v_lshlrev_b32_e32 v3, 2, v0
	v_lshlrev_b32_e32 v172, 3, v2
	v_lshl_or_b32 v2, v1, 6, v170
	v_and_b32_e32 v3, 32, v3
	v_bitop3_b32 v4, v2, s1, v3 bitop3:0xde
	v_lshlrev_b32_e32 v2, 6, v0
	s_movk_i32 s1, 0x3c0
	s_cmpk_lt_u32 s0, 0x100
	v_and_or_b32 v2, v2, s1, v170
	s_cselect_b64 s[46:47], -1, 0
	s_and_b32 s0, s0, 0xffffff00
	v_bitop3_b32 v173, s10, v2, v3 bitop3:0xf6
	s_lshl_b32 s86, s36, 6
	v_or_b32_e32 v2, s0, v178
	v_or_b32_e32 v192, s86, v2
	v_and_b32_e32 v2, 3, v0
	v_add_u32_e32 v174, 26, v2
	v_lshl_add_u64 v[2:3], s[12:13], 0, v[170:171]
	s_mov_b64 s[0:1], 0xf800000
	v_lshl_add_u64 v[176:177], v[2:3], 0, s[0:1]
	v_lshlrev_b32_e32 v2, 8, v0
	v_and_b32_e32 v2, 0x18000, v2
	v_lshlrev_b32_e32 v3, 11, v12
	s_or_b32 s87, s52, 0x190
	s_add_i32 s0, s63, 0xfffff380
	v_or3_b32 v2, v10, v2, v3
	s_add_u32 s48, s28, 0x15370000
	v_add_u32_e32 v180, v2, v11
	v_lshlrev_b32_e32 v2, 4, v13
	s_addc_u32 s49, s29, 0
	v_and_b32_e32 v2, 0x38000, v2
	s_waitcnt vmcnt(6)
	s_add_u32 s50, s28, 0x15280000
	v_or3_b32 v2, v10, v2, v3
	s_mov_b32 s45, 0
	v_lshl_or_b32 v175, s36, 5, v172
	s_addc_u32 s51, s29, 0
	v_add_u32_e32 v182, v2, v11
	s_add_i32 s89, 0, 0x10000
	s_add_i32 s90, 0, 0x14000
	v_mbcnt_lo_u32_b32 v2, -1, 0
	v_or_b32_e32 v179, 0xfffffb80, v175
	v_add_u32_e32 v193, 0x200, v192
	v_add_u32_e32 v194, 0x400, v192
	v_add_u32_e32 v195, 0x600, v192
	v_or_b32_e32 v196, -4, v0
	s_mov_b32 s37, s45
	v_writelane_b32 v246, s63, 19
	v_mov_b32_e32 v181, v171
	v_mov_b32_e32 v183, v171
	v_add_u32_e32 v197, s89, v173
	v_add_u32_e32 v198, s90, v173
	v_add_u32_e32 v199, 0, v4
	s_movk_i32 s76, 0x80
	s_movk_i32 s92, 0xfb10
	s_mov_b32 s88, 0x34a0000
	s_movk_i32 s94, 0x7fff
	s_mov_b32 s95, 0x8080
	s_movk_i32 s93, 0xfe1
	v_mov_b32_e32 v200, 0x358637bd
	v_mov_b32_e32 v201, 0xfffff01e
	v_mov_b32_e32 v202, 0x3e38aa3b
	v_mbcnt_hi_u32_b32 v203, -1, v2
	v_mov_b32_e32 v204, 0x3000000
	s_mov_b32 s1, s30
	s_mov_b32 s14, 0
	s_barrier
	v_writelane_b32 v246, s0, 20
	s_waitcnt vmcnt(0)
	s_branch .LBB0_362

.LBB0_817:
	v_readlane_b32 s20, v246, 2
	v_readlane_b32 s21, v246, 3
	s_add_u32 s16, s20, 0xb600000
	s_addc_u32 s17, s21, 0
	s_add_u32 s18, s20, 0xb600400
	s_addc_u32 s19, s21, 0
	s_add_u32 s20, s20, 0x7500000
	s_mov_b64 s[22:23], 0x80
	s_addc_u32 s21, s21, 0
	s_add_i32 m0, s5, 0x18000
	v_lshl_add_u64 v[10:11], v[10:11], 0, s[22:23]
	global_load_lds_dwordx4 v[10:11], off
	v_lshl_add_u64 v[6:7], v[6:7], 0, s[22:23]
	s_add_i32 m0, s5, 0x1a000
	s_add_i32 s49, s5, 0x8000
	global_load_lds_dwordx4 v[6:7], off
	v_lshl_add_u64 v[6:7], v[8:9], 0, s[22:23]
	s_mov_b32 m0, s49
	s_add_i32 s50, s5, 0xa000
	global_load_lds_dwordx4 v[6:7], off
	v_lshl_add_u64 v[6:7], v[12:13], 0, s[22:23]
	s_mov_b32 m0, s50
	v_lshl_add_u64 v[4:5], v[4:5], 0, s[22:23]
	global_load_lds_dwordx4 v[6:7], off
	s_add_i32 m0, s5, 0x1c000
	v_lshl_add_u64 v[2:3], v[2:3], 0, s[22:23]
	global_load_lds_dwordx4 v[4:5], off
	s_add_i32 m0, s5, 0x1e000
	s_lshr_b32 s7, s7, 26
	global_load_lds_dwordx4 v[2:3], off
	s_waitcnt vmcnt(8)
	s_barrier
	v_and_b32_e32 v1, 15, v0
	s_add_i32 s7, s6, s7
	v_lshlrev_b32_e32 v2, 1, v18
	s_ashr_i32 s51, s7, 6
	v_lshl_or_b32 v3, v1, 6, v2
	s_lshl_b32 s7, s28, 13
	v_and_b32_e32 v4, 32, v180
	v_bitop3_b32 v3, v3, s7, v4 bitop3:0xde
	s_lshl_b32 s7, s25, 5
	s_and_b32 s7, s7, 0x60
	v_lshlrev_b32_e32 v5, 6, v0
	s_movk_i32 s25, 0x3c0
	v_and_or_b32 v2, v5, s25, v2
	s_lshl_b32 s25, s7, 7
	v_bitop3_b32 v181, s25, v2, v4 bitop3:0xf6
	v_add_u32_e32 v2, v22, v18
	v_add3_u32 v2, v2, v16, v17
	v_mul_lo_u32 v2, s6, v2
	v_lshlrev_b32_e32 v2, 1, v2
	v_add3_u32 v140, v14, v2, v15
	v_add_u32_e32 v2, v23, v18
	v_add3_u32 v2, v2, v16, v17
	v_mul_lo_u32 v2, s6, v2
	s_add_i32 s52, s51, -2
	v_lshlrev_b32_e32 v2, 1, v2
	s_cmpk_lt_u32 s24, 0x100
	v_add3_u32 v144, v14, v2, v15
	v_add_u32_e32 v2, v20, v19
	s_cselect_b64 s[24:25], -1, 0
	s_or_b32 s53, s31, 1
	v_mul_lo_u32 v2, s6, v2
	v_lshl_or_b32 v179, s28, 6, v1
	s_mul_hi_u32 s28, s10, s53
	v_lshlrev_b32_e32 v2, 1, v2
	s_add_i32 s28, s28, s29
	s_mul_i32 s29, s11, s53
	v_add3_u32 v148, v14, v2, v15
	v_add_u32_e32 v2, v21, v19
	s_or_b32 s54, s86, -4
	s_add_i32 s28, s28, s29
	s_mul_i32 s29, s10, s53
	v_mul_lo_u32 v2, s6, v2
	s_waitcnt vmcnt(6)
	s_add_u32 s55, s26, s29
	v_lshlrev_b32_e32 v2, 1, v2
	s_addc_u32 s56, s27, s28
	v_mov_b32_e32 v141, v139
	v_mov_b32_e32 v145, v139
	v_mov_b32_e32 v149, v139
	v_add3_u32 v152, v14, v2, v15
	v_mov_b32_e32 v153, v139
	s_add_i32 s57, 0, 0x10000
	s_add_i32 s58, 0, 0x14000
	v_or_b32_e32 v184, s7, v18
	v_lshl_add_u64 v[142:143], s[8:9], 0, v[140:141]
	v_lshl_add_u64 v[146:147], s[8:9], 0, v[144:145]
	v_lshl_add_u64 v[150:151], s[8:9], 0, v[148:149]
	v_lshl_add_u64 v[154:155], s[8:9], 0, v[152:153]
	s_mov_b64 s[42:43], -1
	v_add_u32_e32 v185, s57, v181
	v_add_u32_e32 v186, s58, v181
	v_add_u32_e32 v187, 0, v3
	s_mov_b64 s[26:27], 0x100
	s_mov_b64 s[28:29], 0x180
	s_mov_b32 s30, 0x3b808081
	s_mov_b64 s[34:35], s[36:37]
	s_barrier
	s_branch .LBB0_820

.LBB0_899:
	v_readlane_b32 s20, v246, 2
	v_readlane_b32 s21, v246, 3
	s_add_u32 s18, s20, 0xb600000
	s_addc_u32 s19, s21, 0
	s_add_u32 s20, s20, 0x1bb00000
	s_mov_b64 s[22:23], 0x80
	s_addc_u32 s21, s21, 0
	s_and_b32 s43, s7, 3
	s_add_i32 m0, s39, 0x18000
	v_lshl_add_u64 v[8:9], v[8:9], 0, s[22:23]
	s_lshl_b32 s7, s6, 13
	s_lshl_b32 s26, s43, 12
	global_load_lds_dwordx4 v[8:9], off
	v_lshl_add_u64 v[6:7], v[6:7], 0, s[22:23]
	s_add_i32 m0, s39, 0x1a000
	s_add_i32 s44, s39, 0x8000
	s_add_i32 s45, s39, 0xa000
	global_load_lds_dwordx4 v[6:7], off
	v_lshl_add_u64 v[2:3], v[2:3], 0, s[22:23]
	s_mov_b32 m0, s44
	s_add_u32 s24, s8, 0x40080
	global_load_lds_dwordx4 v[2:3], off
	v_lshl_add_u64 v[2:3], v[4:5], 0, s[22:23]
	s_mov_b32 m0, s45
	s_addc_u32 s25, s9, 0
	global_load_lds_dwordx4 v[2:3], off
	s_add_i32 m0, s39, 0x1c000
	v_lshl_add_u64 v[2:3], s[24:25], 0, v[184:185]
	global_load_lds_dwordx4 v[2:3], off
	v_lshl_add_u64 v[2:3], s[24:25], 0, v[188:189]
	s_add_i32 m0, s39, 0x1e000
	v_and_b32_e32 v1, 15, v0
	global_load_lds_dwordx4 v[2:3], off
	s_waitcnt vmcnt(8)
	s_barrier
	v_bfe_u32 v2, v0, 4, 2
	v_lshlrev_b32_e32 v4, 4, v2
	v_lshl_or_b32 v206, s6, 6, v1
	v_lshl_or_b32 v5, v1, 6, v4
	v_and_b32_e32 v6, 32, v180
	v_lshlrev_b32_e32 v7, 6, v0
	s_movk_i32 s6, 0x3c0
	v_lshlrev_b32_e32 v3, 3, v2
	v_bitop3_b32 v5, v5, s7, v6 bitop3:0xde
	v_and_or_b32 v4, v7, s6, v4
	v_cmp_eq_u32_e64 s[6:7], 0, v2
	v_lshlrev_b32_e32 v2, 8, v0
	v_lshl_or_b32 v208, s43, 5, v3
	v_and_b32_e32 v2, 0x18000, v2
	v_lshlrev_b32_e32 v3, 11, v12
	v_or3_b32 v2, v10, v2, v3
	v_add_u32_e32 v190, v2, v11
	v_lshlrev_b32_e32 v2, 4, v13
	v_and_b32_e32 v2, 0x38000, v2
	s_waitcnt vmcnt(6)
	s_cmpk_lt_u32 s0, 0x100
	v_or3_b32 v2, v10, v2, v3
	v_bitop3_b32 v207, s26, v4, v6 bitop3:0xf6
	s_cselect_b64 s[24:25], -1, 0
	v_add_u32_e32 v192, v2, v11
	s_add_i32 s48, 0, 0x10000
	s_add_i32 s49, 0, 0x14000
	v_mbcnt_lo_u32_b32 v2, -1, 0
	v_lshrrev_b32_e32 v181, 4, v0
	s_or_b32 s46, s36, 1
	s_or_b32 s47, s86, -4
	v_mov_b32_e32 v191, v185
	v_mov_b32_e32 v193, v185
	s_mov_b64 s[26:27], -1
	v_add_u32_e32 v209, s48, v207
	v_add_u32_e32 v210, s49, v207
	v_add_u32_e32 v211, 0, v5
	v_mbcnt_hi_u32_b32 v179, -1, v2
	s_barrier
	s_branch .LBB0_902

.LBB0_985:
	v_readlane_b32 s34, v246, 2
	v_readlane_b32 s35, v246, 3
	s_add_u32 s26, s34, 0xf800000
	s_mov_b64 s[28:29], 0x80
	s_addc_u32 s27, s35, 0
	s_and_b32 s4, s3, 3
	s_add_i32 m0, s54, 0x18000
	v_lshl_add_u64 v[8:9], v[8:9], 0, s[28:29]
	s_lshl_b32 s58, s33, 1
	s_lshl_b32 s5, s1, 13
	s_lshl_b32 s7, s4, 12
	s_and_b32 s59, s2, -2
	global_load_lds_dwordx4 v[8:9], off
	v_lshl_add_u64 v[6:7], v[6:7], 0, s[28:29]
	s_add_i32 m0, s54, 0x1a000
	s_add_i32 s60, s54, 0x8000
	s_add_i32 s61, s54, 0xa000
	global_load_lds_dwordx4 v[6:7], off
	v_lshl_add_u64 v[2:3], v[2:3], 0, s[28:29]
	s_mov_b32 m0, s60
	s_add_u32 s2, s10, 0x40080
	global_load_lds_dwordx4 v[2:3], off
	v_lshl_add_u64 v[2:3], v[4:5], 0, s[28:29]
	s_mov_b32 m0, s61
	s_addc_u32 s3, s11, 0
	global_load_lds_dwordx4 v[2:3], off
	s_add_i32 m0, s54, 0x1c000
	v_lshl_add_u64 v[2:3], s[2:3], 0, v[184:185]
	global_load_lds_dwordx4 v[2:3], off
	v_lshl_add_u64 v[2:3], s[2:3], 0, v[188:189]
	s_add_i32 m0, s54, 0x1e000
	v_and_b32_e32 v179, 15, v0
	global_load_lds_dwordx4 v[2:3], off
	s_waitcnt vmcnt(8)
	s_barrier
	v_bfe_u32 v2, v0, 4, 2
	v_lshl_or_b32 v212, s1, 6, v179
	v_lshlrev_b32_e32 v3, 3, v2
	v_lshlrev_b32_e32 v2, 4, v2
	v_lshlrev_b32_e32 v6, 6, v0
	s_movk_i32 s1, 0x3c0
	s_cmpk_lt_u32 s0, 0x100
	v_and_or_b32 v6, v6, s1, v2
	s_cselect_b64 s[30:31], -1, 0
	s_and_b32 s0, s0, 0xffffff00
	s_lshl_b32 s1, s4, 6
	v_lshl_or_b32 v214, s4, 5, v3
	s_or_b32 s0, s1, s0
	v_mov_b32_e32 v3, v185
	v_lshl_or_b32 v4, v179, 6, v2
	v_or3_b32 v215, s0, v2, v179
	v_lshl_add_u64 v[2:3], s[34:35], 0, v[2:3]
	s_mov_b64 s[0:1], 0x1bb00000
	v_lshl_add_u64 v[190:191], v[2:3], 0, s[0:1]
	v_lshlrev_b32_e32 v2, 8, v0
	v_and_b32_e32 v2, 0x18000, v2
	v_lshlrev_b32_e32 v3, 11, v12
	v_or3_b32 v2, v10, v2, v3
	v_add_u32_e32 v192, v2, v11
	v_lshlrev_b32_e32 v2, 4, v13
	v_and_b32_e32 v2, 0x38000, v2
	v_and_b32_e32 v5, 32, v180
	s_waitcnt vmcnt(6)
	s_add_u32 s34, s34, 0x3e40
	v_or3_b32 v2, v10, v2, v3
	v_bitop3_b32 v4, v4, s5, v5 bitop3:0xde
	v_bitop3_b32 v213, s7, v6, v5 bitop3:0xf6
	s_addc_u32 s35, s35, 0
	v_add_u32_e32 v194, v2, v11
	s_add_i32 s62, 0, 0x10000
	s_add_i32 s63, 0, 0x14000
	v_mbcnt_lo_u32_b32 v2, -1, 0
	v_lshrrev_b32_e32 v1, 4, v0
	v_add_u32_e32 v216, 0x200, v215
	v_add_u32_e32 v217, 0x400, v215
	v_add_u32_e32 v218, 0x600, v215
	v_mov_b32_e32 v193, v185
	v_mov_b32_e32 v195, v185
	v_add_u32_e32 v219, s62, v213
	v_add_u32_e32 v220, s63, v213
	v_add_u32_e32 v221, 0, v4
	s_movk_i32 s64, 0x80
	s_movk_i32 s65, 0x1550
	s_movk_i32 s66, 0x154f
	s_movk_i32 s67, 0xfb10
	v_mbcnt_hi_u32_b32 v181, -1, v2
	v_mov_b32_e32 v222, 0x358637bd
	s_movk_i32 s68, 0x1600
	s_mov_b32 s69, 0x34a0000
	s_add_i32 s70, 0, 0x201ac
	s_mov_b32 s0, s52
	s_mov_b32 s72, 0
	s_waitcnt vmcnt(8)
	v_add_f32_e32 v114, v114, v115
	v_add_f32_e32 v116, v116, v117
	v_add_f32_e32 v118, v118, v119
	v_add_f32_e32 v120, v120, v121
	v_add_f32_e32 v122, v122, v123
	v_add_f32_e32 v124, v124, v125
	v_add_f32_e32 v126, v126, v127
	v_add_f32_e32 v128, v128, v129
	v_add_f32_e32 v114, v114, v116
	v_add_f32_e32 v118, v118, v120
	v_add_f32_e32 v122, v122, v124
	v_add_f32_e32 v126, v126, v128
	v_add_f32_e32 v114, v114, v118
	v_add_f32_e32 v122, v122, v126
	v_add_f32_e32 v114, v114, v122
	v_fmamk_f32 v114, v114, 0x3a800000, v222
	v_rsq_f32_e32 v114, v114
	v_mov_b32_e32 v131, 0x21000
	v_lshl_add_u32 v131, v0, 2, v131
	ds_write_b32 v131, v114
	s_waitcnt lgkmcnt(0)
	s_barrier
	s_branch .LBB0_988

.LBB0_1102:
	v_readlane_b32 s12, v246, 2
	v_readlane_b32 s13, v246, 3
	s_add_u32 s12, s12, 0xb600000
	s_addc_u32 s13, s13, 0
	s_lshl_b32 s0, s0, 5
	s_mov_b64 s[14:15], 0x80
	s_and_b32 s26, s0, 0x60
	s_add_i32 m0, s4, 0x18000
	v_lshl_add_u64 v[8:9], v[8:9], 0, s[14:15]
	s_lshl_b32 s19, s17, 13
	s_lshl_b32 s27, s26, 7
	global_load_lds_dwordx4 v[8:9], off
	v_lshl_add_u64 v[6:7], v[6:7], 0, s[14:15]
	s_add_i32 m0, s4, 0x1a000
	s_add_i32 s0, s4, 0x8000
	s_add_i32 s1, s4, 0xa000
	global_load_lds_dwordx4 v[6:7], off
	v_lshl_add_u64 v[2:3], v[2:3], 0, s[14:15]
	s_mov_b32 m0, s0
	s_add_u32 s20, s24, 0xb0080
	global_load_lds_dwordx4 v[2:3], off
	v_lshl_add_u64 v[2:3], v[4:5], 0, s[14:15]
	s_mov_b32 m0, s1
	s_addc_u32 s21, s25, 0
	global_load_lds_dwordx4 v[2:3], off
	s_add_i32 m0, s4, 0x1c000
	v_lshl_add_u64 v[2:3], s[20:21], 0, v[134:135]
	global_load_lds_dwordx4 v[2:3], off
	v_lshl_add_u64 v[2:3], s[20:21], 0, v[130:131]
	s_add_i32 m0, s4, 0x1e000
	v_and_b32_e32 v1, 15, v0
	global_load_lds_dwordx4 v[2:3], off
	s_waitcnt vmcnt(8)
	s_barrier
	v_lshl_or_b32 v148, s17, 6, v1
	v_lshlrev_b32_e32 v2, 1, v10
	v_lshlrev_b32_e32 v5, 6, v0
	s_movk_i32 s17, 0x3c0
	s_cmpk_lt_u32 s16, 0x100
	v_lshl_or_b32 v3, v1, 6, v2
	v_and_or_b32 v2, v5, s17, v2
	s_cselect_b64 s[16:17], -1, 0
	s_or_b32 s31, s28, 1
	v_and_b32_e32 v4, 32, v180
	s_or_b32 s33, s86, -4
	s_mul_i32 s20, s31, 0x160000
	v_bitop3_b32 v3, v3, s19, v4 bitop3:0xde
	s_mul_hi_i32 s19, s31, 0x160000
	s_add_u32 s34, s7, s20
	v_bitop3_b32 v2, s27, v2, v4 bitop3:0xf6
	s_waitcnt vmcnt(6)
	s_addc_u32 s35, s18, s19
	v_add_u16_e32 v4, v11, v12
	s_add_i32 s38, 0, 0x10000
	s_add_i32 s40, 0, 0x14000
	s_add_i32 s42, 0, 0x18000
	s_add_i32 s44, 0, 0x1c000
	v_lshrrev_b16_e32 v4, 1, v4
	v_add_u32_e32 v150, s38, v2
	v_add_u32_e32 v151, s40, v2
	s_add_i32 s38, s38, s6
	s_add_i32 s40, s40, s6
	v_add_u32_e32 v153, s42, v2
	v_add_u32_e32 v154, s44, v2
	s_add_i32 s42, s42, s6
	s_add_i32 s44, s44, s6
	v_or_b32_e32 v149, s26, v10
	v_add_lshl_u32 v138, v14, v4, 1
	v_mov_b32_e32 v139, v135
	v_add_lshl_u32 v140, v13, v4, 1
	v_mov_b32_e32 v141, v135
	s_mov_b64 s[26:27], -1
	v_add_u32_e32 v152, 0, v3
	s_add_i32 s36, s4, 0xc000
	s_add_i32 s37, s4, 0xe000
	s_add_i32 s39, s38, 0x2000
	s_add_i32 s41, s40, 0x2000
	s_add_i32 s43, s42, 0x2000
	s_add_i32 s45, s44, 0x2000
	s_mov_b64 s[18:19], s[24:25]
	s_barrier
	s_branch .LBB0_1105
